# GEMM LDS-DMA issue order: the four A-tile loads of a k-step first, then the four B-tile loads (was interleaved A,B)
# baseline (speedup 1.0000x reference)
; __device__ __forceinline__ int opaque_tid() { int t = threadIdx.x; asm volatile("" : "+v"(t)); return t; }
; template <class Epi>
; __device__ __forceinline__ void gemm_tile(const bf16_t* A, int lda, const bf16_t* Bt, int ldb, int K, int m0, int n0, const Epi& epi, char* smem) {
;     const int tid = opaque_tid(), lane = tid & 63, wid = tid >> 6, wr = wid >> 1, wc = wid & 1, fr = lane & 15, fq = lane >> 4;
;     f32x4 acc[4][4];
; #pragma unroll
;     for (int m = 0; m < 4; ++m)
; #pragma unroll
;         for (int n = 0; n < 4; ++n) acc[m][n] = (f32x4){0.f, 0.f, 0.f, 0.f};
;     const int lr = lane >> 3;
;     const bf16_t* Ag[4]; const bf16_t* Bg[4];
; #pragma unroll
;     for (int i = 0; i < 4; ++i) {
;         const int r = (wid + 4 * i) * 8 + lr, lc = (lane & 7) ^ ((r >> 1) & 7);
;         Ag[i] = A + (size_t)(m0 + r) * lda + lc * 8; Bg[i] = Bt + (size_t)(n0 + r) * ldb + lc * 8;
;     }
;     const unsigned lds0 = (unsigned)(uintptr_t)smem;
;     const int rsw = (fr >> 1) & 7;
;     const int aofs = (wr * 64 + fr) * 128, bofs = 16384 + (wc * 64 + fr) * 128;
;     const int nk = K >> 6;
;     ...
;     G_ISSUE(0, 0)
;     asm volatile("s_waitcnt vmcnt(0)" ::: "memory");
.LBB0_99:
	s_waitcnt vmcnt(1)
	v_mov_b32_e32 v16, v109
	s_lshl_b32 s43, s35, 7
	v_ashrrev_i32_e32 v17, 6, v16
	v_bfe_u32 v18, v16, 3, 3
	v_lshlrev_b32_e32 v19, 3, v17
	s_waitcnt vmcnt(0)
	v_or_b32_e32 v20, v19, v18
	v_add_u32_e32 v2, s43, v20
	v_mov_b64_e32 v[0:1], s[28:29]
	s_movk_i32 s8, 0x1600
	v_lshrrev_b32_e32 v21, 1, v20
	v_mad_i64_i32 v[2:3], s[0:1], v2, s8, v[0:1]
	s_lshl_b32 s42, s34, 7
	v_xor_b32_e32 v4, v21, v16
	v_readlane_b32 s0, v251, 28
	v_lshlrev_b32_e32 v4, 4, v4
	v_add_u32_e32 v6, s42, v20
	v_readlane_b32 s1, v251, 29
	v_add_u32_e32 v10, 32, v20
	v_add_u32_e32 v14, 64, v20
	v_add_u32_e32 v20, 0x60, v20
	v_and_b32_e32 v104, 0x70, v4
	v_mov_b64_e32 v[4:5], s[0:1]
	v_add_u32_e32 v8, s43, v10
	v_add_u32_e32 v10, s42, v10
	v_add_u32_e32 v12, s43, v14
	v_add_u32_e32 v14, s42, v14
	v_add_u32_e32 v22, s43, v20
	v_add_u32_e32 v20, s42, v20
	v_mad_i64_i32 v[6:7], s[0:1], v6, s8, v[4:5]
	v_mad_i64_i32 v[8:9], s[0:1], v8, s8, v[0:1]
	v_mad_i64_i32 v[10:11], s[0:1], v10, s8, v[4:5]
	v_mad_i64_i32 v[12:13], s[0:1], v12, s8, v[0:1]
	v_mad_i64_i32 v[14:15], s[0:1], v14, s8, v[4:5]
	v_mad_i64_i32 v[0:1], s[0:1], v22, s8, v[0:1]
	v_mad_i64_i32 v[4:5], s[0:1], v20, s8, v[4:5]
	v_lshlrev_b32_e32 v84, 10, v17
	v_lshl_add_u64 v[2:3], v[2:3], 0, v[104:105]
	v_readfirstlane_b32 s0, v84
	s_mov_b32 m0, s0
	v_lshl_add_u64 v[6:7], v[6:7], 0, v[104:105]
	global_load_lds_dwordx4 v[2:3], off
	v_add_u32_e32 v2, 0x4000, v84
	v_lshl_add_u64 v[8:9], v[8:9], 0, v[104:105]
	v_readfirstlane_b32 s0, v2
	v_add_u32_e32 v2, 0x1000, v84
	s_mov_b32 m0, s0
	v_readfirstlane_b32 s0, v2
	v_add_u32_e32 v2, 0x5000, v84
	global_load_lds_dwordx4 v[6:7], off
	s_mov_b32 m0, s0
	v_readfirstlane_b32 s0, v2
	v_add_u32_e32 v2, 0x2000, v84
	v_lshl_add_u64 v[10:11], v[10:11], 0, v[104:105]
	global_load_lds_dwordx4 v[8:9], off
	s_mov_b32 m0, s0
	v_readfirstlane_b32 s0, v2
	v_add_u32_e32 v2, 0x6000, v84
	v_lshl_add_u64 v[12:13], v[12:13], 0, v[104:105]
	global_load_lds_dwordx4 v[10:11], off
	s_mov_b32 m0, s0
	v_readfirstlane_b32 s0, v2
	v_add_u32_e32 v2, 0x3000, v84
	v_lshl_add_u64 v[14:15], v[14:15], 0, v[104:105]
	global_load_lds_dwordx4 v[12:13], off
	s_mov_b32 m0, s0
	v_readfirstlane_b32 s0, v2
	v_lshl_add_u64 v[0:1], v[0:1], 0, v[104:105]
	global_load_lds_dwordx4 v[14:15], off
	s_mov_b32 m0, s0
	v_lshl_add_u64 v[4:5], v[4:5], 0, v[104:105]
	global_load_lds_dwordx4 v[0:1], off
	v_add_u32_e32 v0, 0x7000, v84
	v_and_b32_e32 v83, 15, v16
	v_readfirstlane_b32 s0, v0
	s_mov_b32 m0, s0
	v_bfe_u32 v81, v16, 4, 2
	global_load_lds_dwordx4 v[4:5], off
	v_lshrrev_b32_e32 v1, 1, v16
	v_bfe_u32 v2, v16, 1, 3
	v_ashrrev_i32_e32 v82, 7, v16
	v_and_b32_e32 v80, 1, v17
	v_lshlrev_b32_e32 v0, 7, v83
	v_bitop3_b32 v1, v81, v1, 7 bitop3:0x78
	v_bitop3_b32 v2, v81, v2, 4 bitop3:0x36
	v_lshl_or_b32 v3, v80, 13, v0
	v_lshl_or_b32 v0, v82, 13, v0
	v_lshlrev_b32_e32 v1, 4, v1
	v_lshlrev_b32_e32 v2, 4, v2
	v_or_b32_e32 v88, v0, v1
	v_or_b32_e32 v86, v0, v2
	v_or_b32_e32 v0, s43, v18
	v_or_b32_e32 v85, v3, v2
	v_add_u32_e32 v0, v0, v19
	v_bitop3_b32 v2, v21, 7, v16 bitop3:0x48
	v_or_b32_e32 v87, v3, v1
	v_mad_i64_i32 v[0:1], s[0:1], v0, s8, 0
	v_lshlrev_b32_e32 v2, 4, v2
	v_readlane_b32 s4, v252, 51
	v_or_b32_e32 v0, v0, v2
	v_readlane_b32 s5, v252, 52
	v_readlane_b32 s6, v252, 53
	v_readlane_b32 s7, v252, 54
	v_lshl_add_u64 v[64:65], s[4:5], 0, v[0:1]
	v_or_b32_e32 v0, s42, v18
	v_add_u32_e32 v0, v0, v19
	v_mad_i64_i32 v[0:1], s[0:1], v0, s8, 0
	v_or_b32_e32 v0, v0, v2
	v_or_b32_e32 v3, 32, v18
	v_lshl_add_u64 v[66:67], s[6:7], 0, v[0:1]
	v_or_b32_e32 v0, s43, v3
	v_add_u32_e32 v0, v0, v19
	v_mad_i64_i32 v[0:1], s[0:1], v0, s8, 0
	v_or_b32_e32 v0, v0, v2
	v_lshl_add_u64 v[68:69], s[4:5], 0, v[0:1]
	v_or_b32_e32 v0, s42, v3
	v_add_u32_e32 v0, v0, v19
	v_mad_i64_i32 v[0:1], s[0:1], v0, s8, 0
	v_or_b32_e32 v0, v0, v2
	v_or_b32_e32 v3, 64, v18
	v_lshl_add_u64 v[70:71], s[6:7], 0, v[0:1]
	v_or_b32_e32 v0, s43, v3
	v_add_u32_e32 v0, v0, v19
	v_mad_i64_i32 v[0:1], s[0:1], v0, s8, 0
	v_or_b32_e32 v0, v0, v2
	v_lshl_add_u64 v[72:73], s[4:5], 0, v[0:1]
	v_or_b32_e32 v0, s42, v3
	v_add_u32_e32 v0, v0, v19
	v_mad_i64_i32 v[0:1], s[0:1], v0, s8, 0
	v_or_b32_e32 v0, v0, v2
	v_or_b32_e32 v3, 0x60, v18
	v_lshl_add_u64 v[74:75], s[6:7], 0, v[0:1]
	v_or_b32_e32 v0, s43, v3
	v_add_u32_e32 v0, v0, v19
	v_mad_i64_i32 v[0:1], s[0:1], v0, s8, 0
	v_or_b32_e32 v0, v0, v2
	v_lshl_add_u64 v[76:77], s[4:5], 0, v[0:1]
	v_or_b32_e32 v0, s42, v3
	v_add_u32_e32 v0, v0, v19
	v_mad_i64_i32 v[0:1], s[0:1], v0, s8, 0
	s_waitcnt vmcnt(0)
; template <class Epi>
; __device__ __forceinline__ void gemm_tile(const bf16_t* A, int lda, const bf16_t* Bt, int ldb, int K, int m0, int n0, const Epi& epi, char* smem) {
;     ...
;     G_ISSUE(0, 0)
;     asm volatile("s_waitcnt vmcnt(0)" ::: "memory");
;     __syncthreads();
;     for (int kt = 0; kt < nk; ++kt) {
;         const int st = (kt & 1) * 32768;
;         if (kt + 1 < nk) G_ISSUE(((kt + 1) & 1) * 32768, (kt + 1) * 64)
;         {
;             bf16x8 a0[4], b0[4], a1[4], b1[4];
;             const int ch0 = ((0 + fq) ^ rsw) << 4, ch1 = ((4 + fq) ^ rsw) << 4;
; #pragma unroll
;             for (int m = 0; m < 4; ++m) a0[m] = *(const bf16x8*)(smem + st + aofs + m * 2048 + ch0);
; #pragma unroll
;             for (int n = 0; n < 4; ++n) b0[n] = *(const bf16x8*)(smem + st + bofs + n * 2048 + ch0);
;             __builtin_amdgcn_sched_barrier(0);
; #pragma unroll
;             for (int m = 0; m < 4; ++m) a1[m] = *(const bf16x8*)(smem + st + aofs + m * 2048 + ch1);
; #pragma unroll
;             for (int n = 0; n < 4; ++n) b1[n] = *(const bf16x8*)(smem + st + bofs + n * 2048 + ch1);
;             __builtin_amdgcn_sched_barrier(0);
;             __builtin_amdgcn_s_setprio(1);
; #pragma unroll
;             for (int m = 0; m < 4; ++m)
; #pragma unroll
;                 for (int n = 0; n < 4; ++n) acc[m][n] = __builtin_amdgcn_mfma_f32_16x16x32_bf16(b0[n], a0[m], acc[m][n], 0, 0, 0);
;             __builtin_amdgcn_sched_barrier(0);
; #pragma unroll
;             for (int m = 0; m < 4; ++m)
; #pragma unroll
;                 for (int n = 0; n < 4; ++n) acc[m][n] = __builtin_amdgcn_mfma_f32_16x16x32_bf16(b1[n], a1[m], acc[m][n], 0, 0, 0);
;             __builtin_amdgcn_s_setprio(0);
;             __builtin_amdgcn_sched_barrier(0);
;         }
;         asm volatile("s_waitcnt vmcnt(0)" ::: "memory");
;         __syncthreads();
	v_or_b32_e32 v0, v0, v2
	v_lshl_add_u64 v[78:79], s[6:7], 0, v[0:1]
	v_mov_b32_e32 v0, 0
	s_mov_b64 s[0:1], 0
	s_mov_b32 s44, 0x8000
	v_mov_b32_e32 v1, v0
	v_mov_b32_e32 v2, v0
	v_mov_b32_e32 v3, v0
	v_mov_b32_e32 v4, v0
	v_mov_b32_e32 v5, v0
	v_mov_b32_e32 v6, v0
	v_mov_b32_e32 v7, v0
	v_mov_b32_e32 v8, v0
	v_mov_b32_e32 v9, v0
	v_mov_b32_e32 v10, v0
	v_mov_b32_e32 v11, v0
	v_mov_b32_e32 v12, v0
	v_mov_b32_e32 v13, v0
	v_mov_b32_e32 v14, v0
	v_mov_b32_e32 v15, v0
	v_mov_b32_e32 v16, v0
	v_mov_b32_e32 v17, v0
	v_mov_b32_e32 v18, v0
	v_mov_b32_e32 v19, v0
	v_mov_b32_e32 v20, v0
	v_mov_b32_e32 v21, v0
	v_mov_b32_e32 v22, v0
	v_mov_b32_e32 v23, v0
	v_mov_b32_e32 v24, v0
	v_mov_b32_e32 v25, v0
	v_mov_b32_e32 v26, v0
	v_mov_b32_e32 v27, v0
	v_mov_b32_e32 v36, v0
	v_mov_b32_e32 v37, v0
	v_mov_b32_e32 v38, v0
	v_mov_b32_e32 v39, v0
	v_mov_b32_e32 v28, v0
	v_mov_b32_e32 v29, v0
	v_mov_b32_e32 v30, v0
	v_mov_b32_e32 v31, v0
	v_mov_b32_e32 v32, v0
	v_mov_b32_e32 v33, v0
	v_mov_b32_e32 v34, v0
	v_mov_b32_e32 v35, v0
	v_mov_b32_e32 v40, v0
	v_mov_b32_e32 v41, v0
	v_mov_b32_e32 v42, v0
	v_mov_b32_e32 v43, v0
	v_mov_b32_e32 v44, v0
	v_mov_b32_e32 v45, v0
	v_mov_b32_e32 v46, v0
	v_mov_b32_e32 v47, v0
	v_mov_b32_e32 v48, v0
	v_mov_b32_e32 v49, v0
	v_mov_b32_e32 v50, v0
	v_mov_b32_e32 v51, v0
	v_mov_b32_e32 v52, v0
	v_mov_b32_e32 v53, v0
	v_mov_b32_e32 v54, v0
	v_mov_b32_e32 v55, v0
	v_mov_b32_e32 v56, v0
	v_mov_b32_e32 v57, v0
	v_mov_b32_e32 v58, v0
	v_mov_b32_e32 v59, v0
	v_mov_b32_e32 v60, v0
	v_mov_b32_e32 v61, v0
	v_mov_b32_e32 v62, v0
	v_mov_b32_e32 v63, v0
	v_readfirstlane_b32 s98, v84
	s_mov_b64 s[100:101], 0
	s_nop 3
	s_add_u32 s99, s98, 0x8000
	s_mov_b32 m0, s99
	v_lshl_add_u64 v[166:167], v[64:65], 0, s[100:101]
	global_load_lds_dwordx4 v[166:167], off
	s_add_u32 m0, s99, 0x1000
	v_lshl_add_u64 v[166:167], v[68:69], 0, s[100:101]
	global_load_lds_dwordx4 v[166:167], off
	s_add_u32 m0, s99, 0x2000
	v_lshl_add_u64 v[166:167], v[72:73], 0, s[100:101]
	global_load_lds_dwordx4 v[166:167], off
	s_add_u32 m0, s99, 0x3000
	v_lshl_add_u64 v[166:167], v[76:77], 0, s[100:101]
	global_load_lds_dwordx4 v[166:167], off
	s_add_u32 m0, s99, 0x4000
	v_lshl_add_u64 v[166:167], v[66:67], 0, s[100:101]
	global_load_lds_dwordx4 v[166:167], off
	s_add_u32 m0, s99, 0x5000
	v_lshl_add_u64 v[166:167], v[70:71], 0, s[100:101]
	global_load_lds_dwordx4 v[166:167], off
	s_add_u32 m0, s99, 0x6000
	v_lshl_add_u64 v[166:167], v[74:75], 0, s[100:101]
	global_load_lds_dwordx4 v[166:167], off
	s_add_u32 m0, s99, 0x7000
	v_lshl_add_u64 v[166:167], v[78:79], 0, s[100:101]
	global_load_lds_dwordx4 v[166:167], off
	s_waitcnt vmcnt(8) lgkmcnt(0)
	s_barrier
.LBB0_100:
	s_add_i32 s45, s44, 0xffff8000
	s_and_b32 s45, s45, 0x8000
	v_add_u32_e32 v89, s45, v88
	ds_read_b128 v[90:93], v89
	ds_read_b128 v[94:97], v89 offset:2048
	ds_read_b128 v[98:101], v89 offset:4096
	ds_read_b128 v[114:117], v89 offset:6144
	v_or_b32_e32 v89, s45, v87
	ds_read_b128 v[118:121], v89 offset:16384
	ds_read_b128 v[122:125], v89 offset:18432
	ds_read_b128 v[126:129], v89 offset:20480
	ds_read_b128 v[130:133], v89 offset:22528
	v_add_u32_e32 v89, s45, v86
	ds_read_b128 v[134:137], v89
	ds_read_b128 v[138:141], v89 offset:2048
	ds_read_b128 v[142:145], v89 offset:4096
	ds_read_b128 v[146:149], v89 offset:6144
	v_or_b32_e32 v89, s45, v85
	ds_read_b128 v[150:153], v89 offset:16384
	ds_read_b128 v[154:157], v89 offset:18432
	ds_read_b128 v[158:161], v89 offset:20480
	ds_read_b128 v[162:165], v89 offset:22528
	s_waitcnt lgkmcnt(0)
	s_barrier
	s_cmpk_eq_i32 s0, 0x1500
	s_cbranch_scc1 .Lnodma_g100
	s_add_u32 s100, s0, 0x80
	s_addc_u32 s101, s1, 0
	s_add_u32 s99, s98, s45
	s_setprio 1
	v_mfma_f32_16x16x32_bf16 v[36:39], v[118:121], v[90:93], v[36:39]
	v_mfma_f32_16x16x32_bf16 v[24:27], v[122:125], v[90:93], v[24:27]
	v_mfma_f32_16x16x32_bf16 v[20:23], v[126:129], v[90:93], v[20:23]
	v_mfma_f32_16x16x32_bf16 v[16:19], v[130:133], v[90:93], v[16:19]
	s_mov_b32 m0, s99
	v_lshl_add_u64 v[166:167], v[64:65], 0, s[100:101]
	global_load_lds_dwordx4 v[166:167], off
	v_mfma_f32_16x16x32_bf16 v[12:15], v[118:121], v[94:97], v[12:15]
	v_mfma_f32_16x16x32_bf16 v[8:11], v[122:125], v[94:97], v[8:11]
	v_mfma_f32_16x16x32_bf16 v[4:7], v[126:129], v[94:97], v[4:7]
	v_mfma_f32_16x16x32_bf16 v[0:3], v[130:133], v[94:97], v[0:3]
	s_add_u32 m0, s99, 0x1000
	v_lshl_add_u64 v[166:167], v[68:69], 0, s[100:101]
	global_load_lds_dwordx4 v[166:167], off
	v_mfma_f32_16x16x32_bf16 v[28:31], v[118:121], v[98:101], v[28:31]
	v_mfma_f32_16x16x32_bf16 v[32:35], v[122:125], v[98:101], v[32:35]
	v_mfma_f32_16x16x32_bf16 v[40:43], v[126:129], v[98:101], v[40:43]
	v_mfma_f32_16x16x32_bf16 v[44:47], v[130:133], v[98:101], v[44:47]
	s_add_u32 m0, s99, 0x2000
	v_lshl_add_u64 v[166:167], v[72:73], 0, s[100:101]
	global_load_lds_dwordx4 v[166:167], off
	v_mfma_f32_16x16x32_bf16 v[48:51], v[118:121], v[114:117], v[48:51]
	v_mfma_f32_16x16x32_bf16 v[52:55], v[122:125], v[114:117], v[52:55]
	v_mfma_f32_16x16x32_bf16 v[56:59], v[126:129], v[114:117], v[56:59]
	v_mfma_f32_16x16x32_bf16 v[60:63], v[130:133], v[114:117], v[60:63]
	s_add_u32 m0, s99, 0x3000
	v_lshl_add_u64 v[166:167], v[76:77], 0, s[100:101]
	global_load_lds_dwordx4 v[166:167], off
	v_mfma_f32_16x16x32_bf16 v[36:39], v[150:153], v[134:137], v[36:39]
	v_mfma_f32_16x16x32_bf16 v[24:27], v[154:157], v[134:137], v[24:27]
	v_mfma_f32_16x16x32_bf16 v[20:23], v[158:161], v[134:137], v[20:23]
	v_mfma_f32_16x16x32_bf16 v[16:19], v[162:165], v[134:137], v[16:19]
	s_add_u32 m0, s99, 0x4000
	v_lshl_add_u64 v[166:167], v[66:67], 0, s[100:101]
	global_load_lds_dwordx4 v[166:167], off
	v_mfma_f32_16x16x32_bf16 v[12:15], v[150:153], v[138:141], v[12:15]
	v_mfma_f32_16x16x32_bf16 v[8:11], v[154:157], v[138:141], v[8:11]
	v_mfma_f32_16x16x32_bf16 v[4:7], v[158:161], v[138:141], v[4:7]
	v_mfma_f32_16x16x32_bf16 v[0:3], v[162:165], v[138:141], v[0:3]
	s_add_u32 m0, s99, 0x5000
	v_lshl_add_u64 v[166:167], v[70:71], 0, s[100:101]
	global_load_lds_dwordx4 v[166:167], off
	v_mfma_f32_16x16x32_bf16 v[28:31], v[150:153], v[142:145], v[28:31]
	v_mfma_f32_16x16x32_bf16 v[32:35], v[154:157], v[142:145], v[32:35]
	v_mfma_f32_16x16x32_bf16 v[40:43], v[158:161], v[142:145], v[40:43]
	v_mfma_f32_16x16x32_bf16 v[44:47], v[162:165], v[142:145], v[44:47]
	s_add_u32 m0, s99, 0x6000
	v_lshl_add_u64 v[166:167], v[74:75], 0, s[100:101]
	global_load_lds_dwordx4 v[166:167], off
	v_mfma_f32_16x16x32_bf16 v[48:51], v[150:153], v[146:149], v[48:51]
	v_mfma_f32_16x16x32_bf16 v[52:55], v[154:157], v[146:149], v[52:55]
	v_mfma_f32_16x16x32_bf16 v[56:59], v[158:161], v[146:149], v[56:59]
	v_mfma_f32_16x16x32_bf16 v[60:63], v[162:165], v[146:149], v[60:63]
	s_add_u32 m0, s99, 0x7000
	v_lshl_add_u64 v[166:167], v[78:79], 0, s[100:101]
	global_load_lds_dwordx4 v[166:167], off
	s_setprio 0
	s_branch .Ljoin_g100

; template <class Epi>
; __device__ __forceinline__ void gemm_tile(const bf16_t* A, int lda, const bf16_t* Bt, int ldb, int K, int m0, int n0, const Epi& epi, char* smem) {
;     ...
;     const int lr = lane >> 3;
;     const bf16_t* Ag[4]; const bf16_t* Bg[4];
; #pragma unroll
;     for (int i = 0; i < 4; ++i) {
;         const int r = (wid + 4 * i) * 8 + lr, lc = (lane & 7) ^ ((r >> 1) & 7);
;         Ag[i] = A + (size_t)(m0 + r) * lda + lc * 8; Bg[i] = Bt + (size_t)(n0 + r) * ldb + lc * 8;
;     }
;     const unsigned lds0 = (unsigned)(uintptr_t)smem;
;     const int rsw = (fr >> 1) & 7;
;     const int aofs = (wr * 64 + fr) * 128, bofs = 16384 + (wc * 64 + fr) * 128;
;     const int nk = K >> 6;
;     ...
;     G_ISSUE(0, 0)
; __device__ __forceinline__ bool gemm_unit(int it, int NT, int m_lo, int& mt, int& nt) {
;     const int xcd = blockIdx.x & 7, j = blockIdx.x >> 3, nb = gridDim.x >> 3;
;     const int L = it * nb + j, MX = 34 - m_lo;
;     if (L >= MX * NT) return false;
;     const int grp = L / (8 * NT), r = L - grp * 8 * NT, gsz = min(8, MX - grp * 8);
;     nt = r / gsz; mt = xcd * 34 + m_lo + grp * 8 + (r - nt * gsz);
;     return true;
; }
.LBB0_152:
	s_mul_hi_u32 s1, s0, 0xba2e8ba3
	s_lshr_b32 s1, s1, 8
	s_lshl_b32 s35, s1, 3
	s_sub_i32 s34, s81, s35
	s_min_u32 s42, s34, 8
	s_waitcnt vmcnt(1)
	v_cvt_f32_ubyte0_e32 v0, s42
	v_rcp_iflag_f32_e32 v0, v0
	s_sub_i32 s45, 0, s42
	s_mul_i32 s34, s1, 0xfffffea0
	s_add_i32 s43, s34, s0
	v_mul_f32_e32 v0, 0x4f7ffffe, v0
	v_cvt_u32_f32_e32 v0, v0
	s_abs_i32 s34, s43
	s_ashr_i32 s44, s43, 31
	v_mov_b32_e32 v16, v109
	v_readfirstlane_b32 s46, v0
	s_mul_i32 s45, s45, s46
	s_mul_hi_u32 s45, s46, s45
	s_add_i32 s46, s46, s45
	s_mul_hi_u32 s45, s34, s46
	s_mul_i32 s46, s45, s42
	s_sub_i32 s34, s34, s46
	s_add_i32 s47, s45, 1
	s_sub_i32 s46, s34, s42
	s_cmp_ge_u32 s34, s42
	s_cselect_b32 s45, s47, s45
	s_cselect_b32 s34, s46, s34
	s_add_i32 s46, s45, 1
	s_cmp_ge_u32 s34, s42
	s_cselect_b32 s34, s46, s45
	s_xor_b32 s45, s34, s44
	s_sub_i32 s34, s45, s44
	s_add_i32 s35, s93, s35
	s_mul_i32 s42, s42, s34
	s_add_i32 s35, s35, s43
	s_sub_i32 s35, s35, s42
	v_ashrrev_i32_e32 v17, 6, v16
	v_bfe_u32 v18, v16, 3, 3
	v_lshlrev_b32_e32 v19, 3, v17
	s_lshl_b32 s35, s35, 7
	v_or_b32_e32 v12, v19, v18
	s_waitcnt vmcnt(0)
	v_lshrrev_b32_e32 v20, 1, v12
	v_add_u32_e32 v0, s35, v12
	v_xor_b32_e32 v2, v20, v16
	v_ashrrev_i32_e32 v1, 31, v0
	s_lshl_b32 s43, s34, 7
	v_lshlrev_b64 v[0:1], 11, v[0:1]
	v_lshlrev_b32_e32 v2, 4, v2
	v_add_u32_e32 v6, 32, v12
	v_add_u32_e32 v10, 64, v12
	v_add_u32_e32 v14, 0x60, v12
	v_lshlrev_b32_e32 v84, 10, v17
	v_lshl_add_u64 v[0:1], s[40:41], 0, v[0:1]
	v_and_b32_e32 v104, 0x70, v2
	v_add_u32_e32 v2, s43, v12
	v_add_u32_e32 v4, s35, v6
	v_add_u32_e32 v6, s43, v6
	v_add_u32_e32 v8, s35, v10
	v_add_u32_e32 v10, s43, v10
	v_add_u32_e32 v12, s35, v14
	v_add_u32_e32 v14, s43, v14
	v_readfirstlane_b32 s43, v84
	v_lshl_add_u64 v[0:1], v[0:1], 0, v[104:105]
	v_ashrrev_i32_e32 v3, 31, v2
	v_readlane_b32 s4, v251, 32
	s_mov_b32 m0, s43
	v_lshlrev_b64 v[2:3], 11, v[2:3]
	v_readlane_b32 s5, v251, 33
	v_ashrrev_i32_e32 v5, 31, v4
	global_load_lds_dwordx4 v[0:1], off
	v_add_u32_e32 v0, 0x4000, v84
	v_lshl_add_u64 v[2:3], s[4:5], 0, v[2:3]
	v_lshlrev_b64 v[4:5], 11, v[4:5]
	v_ashrrev_i32_e32 v7, 31, v6
	v_readfirstlane_b32 s43, v0
	v_add_u32_e32 v0, 0x1000, v84
	v_lshl_add_u64 v[2:3], v[2:3], 0, v[104:105]
	v_lshl_add_u64 v[4:5], s[40:41], 0, v[4:5]
	v_lshlrev_b64 v[6:7], 11, v[6:7]
	v_ashrrev_i32_e32 v9, 31, v8
	s_mov_b32 m0, s43
	v_readfirstlane_b32 s43, v0
	v_add_u32_e32 v0, 0x5000, v84
	v_lshl_add_u64 v[4:5], v[4:5], 0, v[104:105]
	v_lshl_add_u64 v[6:7], s[4:5], 0, v[6:7]
	v_lshlrev_b64 v[8:9], 11, v[8:9]
	v_ashrrev_i32_e32 v11, 31, v10
	global_load_lds_dwordx4 v[2:3], off
	s_mov_b32 m0, s43
	v_readfirstlane_b32 s43, v0
	v_add_u32_e32 v0, 0x2000, v84
	v_lshl_add_u64 v[6:7], v[6:7], 0, v[104:105]
	v_lshl_add_u64 v[8:9], s[40:41], 0, v[8:9]
	v_lshlrev_b64 v[10:11], 11, v[10:11]
	v_ashrrev_i32_e32 v13, 31, v12
	global_load_lds_dwordx4 v[4:5], off
	s_mov_b32 m0, s43
	v_readfirstlane_b32 s43, v0
	v_add_u32_e32 v0, 0x6000, v84
	v_lshl_add_u64 v[8:9], v[8:9], 0, v[104:105]
	v_lshl_add_u64 v[10:11], s[4:5], 0, v[10:11]
	v_lshlrev_b64 v[12:13], 11, v[12:13]
	v_ashrrev_i32_e32 v15, 31, v14
	global_load_lds_dwordx4 v[6:7], off
	s_mov_b32 m0, s43
	v_readfirstlane_b32 s43, v0
	v_add_u32_e32 v0, 0x3000, v84
	v_lshl_add_u64 v[10:11], v[10:11], 0, v[104:105]
	v_lshl_add_u64 v[12:13], s[40:41], 0, v[12:13]
	v_lshlrev_b64 v[14:15], 11, v[14:15]
	global_load_lds_dwordx4 v[8:9], off
	s_mov_b32 m0, s43
	v_readfirstlane_b32 s43, v0
	v_add_u32_e32 v0, 0x7000, v84
	v_lshl_add_u64 v[12:13], v[12:13], 0, v[104:105]
	v_lshl_add_u64 v[14:15], s[4:5], 0, v[14:15]
	global_load_lds_dwordx4 v[10:11], off
	s_mov_b32 m0, s43
	v_readfirstlane_b32 s43, v0
	v_lshl_add_u64 v[14:15], v[14:15], 0, v[104:105]
	global_load_lds_dwordx4 v[12:13], off
	s_mov_b32 m0, s43
	s_add_i32 s0, s93, s0
	global_load_lds_dwordx4 v[14:15], off
	v_and_b32_e32 v82, 15, v16
	v_lshrrev_b32_e32 v21, 1, v16
	v_bfe_u32 v83, v16, 4, 2
	s_sub_i32 s0, s0, s42
	s_mulk_i32 s1, 0x158
	v_ashrrev_i32_e32 v80, 7, v16
	v_and_b32_e32 v81, 1, v17
	v_lshlrev_b32_e32 v23, 7, v82
	v_bitop3_b32 v0, v83, v21, 7 bitop3:0x78
	s_sub_i32 s0, s0, s1
	v_bfe_u32 v22, v16, 1, 3
	v_lshlrev_b32_e32 v0, 4, v0
	v_lshl_or_b32 v2, v80, 13, v23
	v_lshl_or_b32 v3, v81, 13, v23
	s_lshl_b32 s0, s0, 7
	v_bitop3_b32 v1, v83, v22, 4 bitop3:0x36
	v_or_b32_e32 v87, v2, v0
	v_or_b32_e32 v88, v3, v0
	v_or_b32_e32 v0, s0, v18
	v_lshlrev_b32_e32 v1, 4, v1
	v_add_u32_e32 v0, v0, v19
	v_or_b32_e32 v86, v2, v1
	v_or_b32_e32 v85, v3, v1
	v_ashrrev_i32_e32 v1, 31, v0
	v_bitop3_b32 v2, v20, 7, v16 bitop3:0x48
	v_lshlrev_b64 v[0:1], 11, v[0:1]
	v_lshlrev_b32_e32 v2, 4, v2
	v_readlane_b32 s4, v252, 55
	v_or_b32_e32 v0, v0, v2
	v_readlane_b32 s5, v252, 56
	s_lshl_b32 s1, s45, 7
	s_lshl_b32 s42, s44, 7
	v_lshl_add_u64 v[64:65], s[4:5], 0, v[0:1]
	v_or_b32_e32 v0, s1, v18
	v_add_u32_e32 v0, v0, v19
	v_subrev_u32_e32 v0, s42, v0
	v_ashrrev_i32_e32 v1, 31, v0
	v_lshlrev_b64 v[0:1], 11, v[0:1]
	v_readlane_b32 s6, v252, 57
	v_or_b32_e32 v0, v0, v2
	v_readlane_b32 s7, v252, 58
	v_or_b32_e32 v3, 32, v18
	s_waitcnt vmcnt(0)
	s_waitcnt vmcnt(0) lgkmcnt(0)
; template <class Epi>
; __device__ __forceinline__ void gemm_tile(const bf16_t* A, int lda, const bf16_t* Bt, int ldb, int K, int m0, int n0, const Epi& epi, char* smem) {
;     ...
;         for (int n = 0; n < 4; ++n) acc[m][n] = (f32x4){0.f, 0.f, 0.f, 0.f};
;     const int lr = lane >> 3;
;     const bf16_t* Ag[4]; const bf16_t* Bg[4];
; #pragma unroll
;     for (int i = 0; i < 4; ++i) {
;         const int r = (wid + 4 * i) * 8 + lr, lc = (lane & 7) ^ ((r >> 1) & 7);
;         Ag[i] = A + (size_t)(m0 + r) * lda + lc * 8; Bg[i] = Bt + (size_t)(n0 + r) * ldb + lc * 8;
;     }
;     const unsigned lds0 = (unsigned)(uintptr_t)smem;
;     const int rsw = (fr >> 1) & 7;
;     const int aofs = (wr * 64 + fr) * 128, bofs = 16384 + (wc * 64 + fr) * 128;
;     const int nk = K >> 6;
;     ...
;     G_ISSUE(0, 0)
;     asm volatile("s_waitcnt vmcnt(0)" ::: "memory");
;     __syncthreads();
;     for (int kt = 0; kt < nk; ++kt) {
;         const int st = (kt & 1) * 32768;
;         if (kt + 1 < nk) G_ISSUE(((kt + 1) & 1) * 32768, (kt + 1) * 64)
	v_lshl_add_u64 v[66:67], s[6:7], 0, v[0:1]
	v_or_b32_e32 v0, s0, v3
	v_add_u32_e32 v0, v0, v19
	v_ashrrev_i32_e32 v1, 31, v0
	v_lshlrev_b64 v[0:1], 11, v[0:1]
	v_or_b32_e32 v0, v0, v2
	v_lshl_add_u64 v[68:69], s[4:5], 0, v[0:1]
	v_or_b32_e32 v0, s1, v3
	v_add_u32_e32 v0, v0, v19
	v_subrev_u32_e32 v0, s42, v0
	v_ashrrev_i32_e32 v1, 31, v0
	v_lshlrev_b64 v[0:1], 11, v[0:1]
	v_or_b32_e32 v0, v0, v2
	v_or_b32_e32 v3, 64, v18
	v_lshl_add_u64 v[70:71], s[6:7], 0, v[0:1]
	v_or_b32_e32 v0, s0, v3
	v_add_u32_e32 v0, v0, v19
	v_ashrrev_i32_e32 v1, 31, v0
	v_lshlrev_b64 v[0:1], 11, v[0:1]
	v_or_b32_e32 v0, v0, v2
	v_lshl_add_u64 v[72:73], s[4:5], 0, v[0:1]
	v_or_b32_e32 v0, s1, v3
	v_add_u32_e32 v0, v0, v19
	v_subrev_u32_e32 v0, s42, v0
	v_ashrrev_i32_e32 v1, 31, v0
	v_lshlrev_b64 v[0:1], 11, v[0:1]
	v_or_b32_e32 v0, v0, v2
	v_or_b32_e32 v3, 0x60, v18
	v_lshl_add_u64 v[74:75], s[6:7], 0, v[0:1]
	v_or_b32_e32 v0, s0, v3
	v_add_u32_e32 v0, v0, v19
	v_ashrrev_i32_e32 v1, 31, v0
	v_lshlrev_b64 v[0:1], 11, v[0:1]
	v_or_b32_e32 v0, v0, v2
	v_lshl_add_u64 v[76:77], s[4:5], 0, v[0:1]
	v_or_b32_e32 v0, s1, v3
	v_add_u32_e32 v0, v0, v19
	v_subrev_u32_e32 v0, s42, v0
	v_ashrrev_i32_e32 v1, 31, v0
	v_lshlrev_b64 v[0:1], 11, v[0:1]
	v_or_b32_e32 v0, v0, v2
	v_lshl_add_u64 v[78:79], s[6:7], 0, v[0:1]
	v_mov_b32_e32 v0, 0
	s_mov_b64 s[0:1], 0
	s_mov_b32 s42, 0x8000
	v_mov_b32_e32 v1, v0
	v_mov_b32_e32 v2, v0
	v_mov_b32_e32 v3, v0
	v_mov_b32_e32 v4, v0
	v_mov_b32_e32 v5, v0
	v_mov_b32_e32 v6, v0
	v_mov_b32_e32 v7, v0
	v_mov_b32_e32 v8, v0
	v_mov_b32_e32 v9, v0
	v_mov_b32_e32 v10, v0
	v_mov_b32_e32 v11, v0
	v_mov_b32_e32 v12, v0
	v_mov_b32_e32 v13, v0
	v_mov_b32_e32 v14, v0
	v_mov_b32_e32 v15, v0
	v_mov_b32_e32 v16, v0
	v_mov_b32_e32 v17, v0
	v_mov_b32_e32 v18, v0
	v_mov_b32_e32 v19, v0
	v_mov_b32_e32 v20, v0
	v_mov_b32_e32 v21, v0
	v_mov_b32_e32 v22, v0
	v_mov_b32_e32 v23, v0
	v_mov_b32_e32 v24, v0
	v_mov_b32_e32 v25, v0
	v_mov_b32_e32 v26, v0
	v_mov_b32_e32 v27, v0
	v_mov_b32_e32 v36, v0
	v_mov_b32_e32 v37, v0
	v_mov_b32_e32 v38, v0
	v_mov_b32_e32 v39, v0
	v_mov_b32_e32 v28, v0
	v_mov_b32_e32 v29, v0
	v_mov_b32_e32 v30, v0
	v_mov_b32_e32 v31, v0
	v_mov_b32_e32 v32, v0
	v_mov_b32_e32 v33, v0
	v_mov_b32_e32 v34, v0
	v_mov_b32_e32 v35, v0
	v_mov_b32_e32 v40, v0
	v_mov_b32_e32 v41, v0
	v_mov_b32_e32 v42, v0
	v_mov_b32_e32 v43, v0
	v_mov_b32_e32 v44, v0
	v_mov_b32_e32 v45, v0
	v_mov_b32_e32 v46, v0
	v_mov_b32_e32 v47, v0
	v_mov_b32_e32 v48, v0
	v_mov_b32_e32 v49, v0
	v_mov_b32_e32 v50, v0
	v_mov_b32_e32 v51, v0
	v_mov_b32_e32 v52, v0
	v_mov_b32_e32 v53, v0
	v_mov_b32_e32 v54, v0
	v_mov_b32_e32 v55, v0
	v_mov_b32_e32 v56, v0
	v_mov_b32_e32 v57, v0
	v_mov_b32_e32 v58, v0
	v_mov_b32_e32 v59, v0
	v_mov_b32_e32 v60, v0
	v_mov_b32_e32 v61, v0
	v_mov_b32_e32 v62, v0
	v_mov_b32_e32 v63, v0
	v_readfirstlane_b32 s98, v84
	s_mov_b64 s[100:101], 0
	s_nop 3
	s_add_u32 s99, s98, 0x8000
	s_mov_b32 m0, s99
	v_lshl_add_u64 v[166:167], v[64:65], 0, s[100:101]
	global_load_lds_dwordx4 v[166:167], off
	s_add_u32 m0, s99, 0x1000
	v_lshl_add_u64 v[166:167], v[68:69], 0, s[100:101]
	global_load_lds_dwordx4 v[166:167], off
	s_add_u32 m0, s99, 0x2000
	v_lshl_add_u64 v[166:167], v[72:73], 0, s[100:101]
	global_load_lds_dwordx4 v[166:167], off
	s_add_u32 m0, s99, 0x3000
	v_lshl_add_u64 v[166:167], v[76:77], 0, s[100:101]
	global_load_lds_dwordx4 v[166:167], off
	s_add_u32 m0, s99, 0x4000
	v_lshl_add_u64 v[166:167], v[66:67], 0, s[100:101]
	global_load_lds_dwordx4 v[166:167], off
	s_add_u32 m0, s99, 0x5000
	v_lshl_add_u64 v[166:167], v[70:71], 0, s[100:101]
	global_load_lds_dwordx4 v[166:167], off
	s_add_u32 m0, s99, 0x6000
	v_lshl_add_u64 v[166:167], v[74:75], 0, s[100:101]
	global_load_lds_dwordx4 v[166:167], off
	s_add_u32 m0, s99, 0x7000
	v_lshl_add_u64 v[166:167], v[78:79], 0, s[100:101]
	global_load_lds_dwordx4 v[166:167], off
	s_waitcnt vmcnt(8) lgkmcnt(0)
	s_barrier
; template <class Epi>
; __device__ __forceinline__ void gemm_tile(const bf16_t* A, int lda, const bf16_t* Bt, int ldb, int K, int m0, int n0, const Epi& epi, char* smem) {
;     ...
;     for (int kt = 0; kt < nk; ++kt) {
;         const int st = (kt & 1) * 32768;
;         if (kt + 1 < nk) G_ISSUE(((kt + 1) & 1) * 32768, (kt + 1) * 64)
;         {
;             bf16x8 a0[4], b0[4], a1[4], b1[4];
;             const int ch0 = ((0 + fq) ^ rsw) << 4, ch1 = ((4 + fq) ^ rsw) << 4;
; #pragma unroll
;             for (int m = 0; m < 4; ++m) a0[m] = *(const bf16x8*)(smem + st + aofs + m * 2048 + ch0);
; #pragma unroll
;             for (int n = 0; n < 4; ++n) b0[n] = *(const bf16x8*)(smem + st + bofs + n * 2048 + ch0);
;             __builtin_amdgcn_sched_barrier(0);
; #pragma unroll
;             for (int m = 0; m < 4; ++m) a1[m] = *(const bf16x8*)(smem + st + aofs + m * 2048 + ch1);
; #pragma unroll
;             for (int n = 0; n < 4; ++n) b1[n] = *(const bf16x8*)(smem + st + bofs + n * 2048 + ch1);
;             __builtin_amdgcn_sched_barrier(0);
;             __builtin_amdgcn_s_setprio(1);
; #pragma unroll
;             for (int m = 0; m < 4; ++m)
; #pragma unroll
;                 for (int n = 0; n < 4; ++n) acc[m][n] = __builtin_amdgcn_mfma_f32_16x16x32_bf16(b0[n], a0[m], acc[m][n], 0, 0, 0);
;             __builtin_amdgcn_sched_barrier(0);
; #pragma unroll
;             for (int m = 0; m < 4; ++m)
; #pragma unroll
;                 for (int n = 0; n < 4; ++n) acc[m][n] = __builtin_amdgcn_mfma_f32_16x16x32_bf16(b1[n], a1[m], acc[m][n], 0, 0, 0);
;             __builtin_amdgcn_s_setprio(0);
;             __builtin_amdgcn_sched_barrier(0);
;         }
;         asm volatile("s_waitcnt vmcnt(0)" ::: "memory");
;         __syncthreads();
.LBB0_153:
	s_add_i32 s43, s42, 0xffff8000
	s_and_b32 s43, s43, 0x8000
	v_add_u32_e32 v89, s43, v87
	ds_read_b128 v[90:93], v89
	ds_read_b128 v[94:97], v89 offset:2048
	ds_read_b128 v[98:101], v89 offset:4096
	ds_read_b128 v[114:117], v89 offset:6144
	v_or_b32_e32 v89, s43, v88
	ds_read_b128 v[118:121], v89 offset:16384
	ds_read_b128 v[122:125], v89 offset:18432
	ds_read_b128 v[126:129], v89 offset:20480
	ds_read_b128 v[130:133], v89 offset:22528
	v_add_u32_e32 v89, s43, v86
	ds_read_b128 v[134:137], v89
	ds_read_b128 v[138:141], v89 offset:2048
	ds_read_b128 v[142:145], v89 offset:4096
	ds_read_b128 v[146:149], v89 offset:6144
	v_or_b32_e32 v89, s43, v85
	ds_read_b128 v[150:153], v89 offset:16384
	ds_read_b128 v[154:157], v89 offset:18432
	ds_read_b128 v[158:161], v89 offset:20480
	ds_read_b128 v[162:165], v89 offset:22528
	s_waitcnt lgkmcnt(0)
	s_barrier
	s_cmpk_eq_i32 s0, 0x700
	s_cbranch_scc1 .Lnodma_g153
	s_add_u32 s100, s0, 0x80
	s_addc_u32 s101, s1, 0
	s_add_u32 s99, s98, s43
	s_setprio 1
	v_mfma_f32_16x16x32_bf16 v[36:39], v[118:121], v[90:93], v[36:39]
	v_mfma_f32_16x16x32_bf16 v[24:27], v[122:125], v[90:93], v[24:27]
	v_mfma_f32_16x16x32_bf16 v[20:23], v[126:129], v[90:93], v[20:23]
	v_mfma_f32_16x16x32_bf16 v[16:19], v[130:133], v[90:93], v[16:19]
	s_mov_b32 m0, s99
	v_lshl_add_u64 v[166:167], v[64:65], 0, s[100:101]
	global_load_lds_dwordx4 v[166:167], off
	v_mfma_f32_16x16x32_bf16 v[12:15], v[118:121], v[94:97], v[12:15]
	v_mfma_f32_16x16x32_bf16 v[8:11], v[122:125], v[94:97], v[8:11]
	v_mfma_f32_16x16x32_bf16 v[4:7], v[126:129], v[94:97], v[4:7]
	v_mfma_f32_16x16x32_bf16 v[0:3], v[130:133], v[94:97], v[0:3]
	s_add_u32 m0, s99, 0x1000
	v_lshl_add_u64 v[166:167], v[68:69], 0, s[100:101]
	global_load_lds_dwordx4 v[166:167], off
	v_mfma_f32_16x16x32_bf16 v[28:31], v[118:121], v[98:101], v[28:31]
	v_mfma_f32_16x16x32_bf16 v[32:35], v[122:125], v[98:101], v[32:35]
	v_mfma_f32_16x16x32_bf16 v[40:43], v[126:129], v[98:101], v[40:43]
	v_mfma_f32_16x16x32_bf16 v[44:47], v[130:133], v[98:101], v[44:47]
	s_add_u32 m0, s99, 0x2000
	v_lshl_add_u64 v[166:167], v[72:73], 0, s[100:101]
	global_load_lds_dwordx4 v[166:167], off
	v_mfma_f32_16x16x32_bf16 v[48:51], v[118:121], v[114:117], v[48:51]
	v_mfma_f32_16x16x32_bf16 v[52:55], v[122:125], v[114:117], v[52:55]
	v_mfma_f32_16x16x32_bf16 v[56:59], v[126:129], v[114:117], v[56:59]
	v_mfma_f32_16x16x32_bf16 v[60:63], v[130:133], v[114:117], v[60:63]
	s_add_u32 m0, s99, 0x3000
	v_lshl_add_u64 v[166:167], v[76:77], 0, s[100:101]
	global_load_lds_dwordx4 v[166:167], off
	v_mfma_f32_16x16x32_bf16 v[36:39], v[150:153], v[134:137], v[36:39]
	v_mfma_f32_16x16x32_bf16 v[24:27], v[154:157], v[134:137], v[24:27]
	v_mfma_f32_16x16x32_bf16 v[20:23], v[158:161], v[134:137], v[20:23]
	v_mfma_f32_16x16x32_bf16 v[16:19], v[162:165], v[134:137], v[16:19]
	s_add_u32 m0, s99, 0x4000
	v_lshl_add_u64 v[166:167], v[66:67], 0, s[100:101]
	global_load_lds_dwordx4 v[166:167], off
	v_mfma_f32_16x16x32_bf16 v[12:15], v[150:153], v[138:141], v[12:15]
	v_mfma_f32_16x16x32_bf16 v[8:11], v[154:157], v[138:141], v[8:11]
	v_mfma_f32_16x16x32_bf16 v[4:7], v[158:161], v[138:141], v[4:7]
	v_mfma_f32_16x16x32_bf16 v[0:3], v[162:165], v[138:141], v[0:3]
	s_add_u32 m0, s99, 0x5000
	v_lshl_add_u64 v[166:167], v[70:71], 0, s[100:101]
	global_load_lds_dwordx4 v[166:167], off
	v_mfma_f32_16x16x32_bf16 v[28:31], v[150:153], v[142:145], v[28:31]
	v_mfma_f32_16x16x32_bf16 v[32:35], v[154:157], v[142:145], v[32:35]
	v_mfma_f32_16x16x32_bf16 v[40:43], v[158:161], v[142:145], v[40:43]
	v_mfma_f32_16x16x32_bf16 v[44:47], v[162:165], v[142:145], v[44:47]
	s_add_u32 m0, s99, 0x6000
	v_lshl_add_u64 v[166:167], v[74:75], 0, s[100:101]
	global_load_lds_dwordx4 v[166:167], off
	v_mfma_f32_16x16x32_bf16 v[48:51], v[150:153], v[146:149], v[48:51]
	v_mfma_f32_16x16x32_bf16 v[52:55], v[154:157], v[146:149], v[52:55]
	v_mfma_f32_16x16x32_bf16 v[56:59], v[158:161], v[146:149], v[56:59]
	v_mfma_f32_16x16x32_bf16 v[60:63], v[162:165], v[146:149], v[60:63]
	s_add_u32 m0, s99, 0x7000
	v_lshl_add_u64 v[166:167], v[78:79], 0, s[100:101]
	global_load_lds_dwordx4 v[166:167], off
	s_setprio 0
	s_branch .Ljoin_g153

; __device__ __forceinline__ int opaque_tid() { int t = threadIdx.x; asm volatile("" : "+v"(t)); return t; }
; template <class Epi>
; __device__ __forceinline__ void gemm_tile(const bf16_t* A, int lda, const bf16_t* Bt, int ldb, int K, int m0, int n0, const Epi& epi, char* smem) {
;     const int tid = opaque_tid(), lane = tid & 63, wid = tid >> 6, wr = wid >> 1, wc = wid & 1, fr = lane & 15, fq = lane >> 4;
;     f32x4 acc[4][4];
; #pragma unroll
;     for (int m = 0; m < 4; ++m)
; #pragma unroll
;         for (int n = 0; n < 4; ++n) acc[m][n] = (f32x4){0.f, 0.f, 0.f, 0.f};
;     const int lr = lane >> 3;
;     const bf16_t* Ag[4]; const bf16_t* Bg[4];
; #pragma unroll
;     for (int i = 0; i < 4; ++i) {
;         const int r = (wid + 4 * i) * 8 + lr, lc = (lane & 7) ^ ((r >> 1) & 7);
;         Ag[i] = A + (size_t)(m0 + r) * lda + lc * 8; Bg[i] = Bt + (size_t)(n0 + r) * ldb + lc * 8;
;     }
;     const unsigned lds0 = (unsigned)(uintptr_t)smem;
;     const int rsw = (fr >> 1) & 7;
;     const int aofs = (wr * 64 + fr) * 128, bofs = 16384 + (wc * 64 + fr) * 128;
;     const int nk = K >> 6;
;     ...
;     G_ISSUE(0, 0)
;     asm volatile("s_waitcnt vmcnt(0)" ::: "memory");
.LBB0_181:
	s_waitcnt vmcnt(1)
	v_mov_b32_e32 v16, v109
	s_lshl_b32 s42, s35, 7
	v_ashrrev_i32_e32 v17, 6, v16
	v_bfe_u32 v18, v16, 3, 3
	v_lshlrev_b32_e32 v19, 3, v17
	s_waitcnt vmcnt(2)
	v_or_b32_e32 v12, v19, v18
	s_waitcnt vmcnt(0)
	v_lshrrev_b32_e32 v20, 1, v12
	s_waitcnt vmcnt(1)
	v_xor_b32_e32 v2, v20, v16
	s_lshl_b32 s44, s34, 7
	v_lshlrev_b32_e32 v2, 4, v2
	s_waitcnt vmcnt(0)
	v_add_u32_e32 v6, 32, v12
	v_add_u32_e32 v10, 64, v12
	v_add_u32_e32 v14, 0x60, v12
	v_add_u32_e32 v0, s42, v12
	v_and_b32_e32 v104, 0x70, v2
	v_add_u32_e32 v2, s44, v12
	v_add_u32_e32 v4, s42, v6
	v_add_u32_e32 v6, s44, v6
	v_add_u32_e32 v8, s42, v10
	v_add_u32_e32 v10, s44, v10
	v_add_u32_e32 v12, s42, v14
	v_add_u32_e32 v14, s44, v14
	v_ashrrev_i32_e32 v1, 31, v0
	v_ashrrev_i32_e32 v3, 31, v2
	v_readlane_b32 s0, v251, 36
	v_ashrrev_i32_e32 v7, 31, v6
	v_ashrrev_i32_e32 v11, 31, v10
	v_ashrrev_i32_e32 v15, 31, v14
	v_lshlrev_b64 v[0:1], 11, v[0:1]
	v_lshlrev_b64 v[2:3], 11, v[2:3]
	v_readlane_b32 s1, v251, 37
	v_lshlrev_b64 v[6:7], 11, v[6:7]
	v_lshlrev_b64 v[10:11], 11, v[10:11]
	v_lshlrev_b64 v[14:15], 11, v[14:15]
	v_lshlrev_b32_e32 v84, 10, v17
	v_lshl_add_u64 v[0:1], s[40:41], 0, v[0:1]
	v_lshl_add_u64 v[2:3], s[0:1], 0, v[2:3]
	v_lshl_add_u64 v[6:7], s[0:1], 0, v[6:7]
	v_lshl_add_u64 v[10:11], s[0:1], 0, v[10:11]
	v_lshl_add_u64 v[14:15], s[0:1], 0, v[14:15]
	v_readfirstlane_b32 s0, v84
	v_lshl_add_u64 v[0:1], v[0:1], 0, v[104:105]
	s_mov_b32 m0, s0
	v_ashrrev_i32_e32 v5, 31, v4
	global_load_lds_dwordx4 v[0:1], off
	v_add_u32_e32 v0, 0x4000, v84
	v_lshlrev_b64 v[4:5], 11, v[4:5]
	v_readfirstlane_b32 s0, v0
	v_add_u32_e32 v0, 0x1000, v84
	v_lshl_add_u64 v[2:3], v[2:3], 0, v[104:105]
	v_lshl_add_u64 v[4:5], s[40:41], 0, v[4:5]
	v_ashrrev_i32_e32 v9, 31, v8
	s_mov_b32 m0, s0
	v_readfirstlane_b32 s0, v0
	v_add_u32_e32 v0, 0x5000, v84
	v_lshl_add_u64 v[4:5], v[4:5], 0, v[104:105]
	v_lshlrev_b64 v[8:9], 11, v[8:9]
	global_load_lds_dwordx4 v[2:3], off
	s_mov_b32 m0, s0
	v_readfirstlane_b32 s0, v0
	v_add_u32_e32 v0, 0x2000, v84
	v_lshl_add_u64 v[6:7], v[6:7], 0, v[104:105]
	v_lshl_add_u64 v[8:9], s[40:41], 0, v[8:9]
	v_ashrrev_i32_e32 v13, 31, v12
	global_load_lds_dwordx4 v[4:5], off
	s_mov_b32 m0, s0
	v_readfirstlane_b32 s0, v0
	v_add_u32_e32 v0, 0x6000, v84
	v_lshl_add_u64 v[8:9], v[8:9], 0, v[104:105]
	v_lshlrev_b64 v[12:13], 11, v[12:13]
	global_load_lds_dwordx4 v[6:7], off
	s_mov_b32 m0, s0
	v_readfirstlane_b32 s0, v0
	v_add_u32_e32 v0, 0x3000, v84
	v_lshl_add_u64 v[10:11], v[10:11], 0, v[104:105]
	v_lshl_add_u64 v[12:13], s[40:41], 0, v[12:13]
	global_load_lds_dwordx4 v[8:9], off
	s_mov_b32 m0, s0
	v_readfirstlane_b32 s0, v0
	v_add_u32_e32 v0, 0x7000, v84
	v_lshl_add_u64 v[12:13], v[12:13], 0, v[104:105]
	global_load_lds_dwordx4 v[10:11], off
	s_mov_b32 m0, s0
	v_readfirstlane_b32 s0, v0
	v_lshl_add_u64 v[14:15], v[14:15], 0, v[104:105]
	global_load_lds_dwordx4 v[12:13], off
	s_mov_b32 m0, s0
	v_and_b32_e32 v83, 15, v16
	global_load_lds_dwordx4 v[14:15], off
	v_bfe_u32 v81, v16, 4, 2
	v_lshrrev_b32_e32 v1, 1, v16
	v_bfe_u32 v2, v16, 1, 3
	v_ashrrev_i32_e32 v82, 7, v16
	v_and_b32_e32 v80, 1, v17
	v_lshlrev_b32_e32 v0, 7, v83
	v_bitop3_b32 v1, v81, v1, 7 bitop3:0x78
	v_bitop3_b32 v2, v81, v2, 4 bitop3:0x36
	v_lshl_or_b32 v3, v80, 13, v0
	v_lshl_or_b32 v0, v82, 13, v0
	v_lshlrev_b32_e32 v1, 4, v1
	v_lshlrev_b32_e32 v2, 4, v2
	v_or_b32_e32 v88, v0, v1
	v_or_b32_e32 v86, v0, v2
	v_or_b32_e32 v0, s42, v18
	v_add_u32_e32 v0, v0, v19
	v_or_b32_e32 v87, v3, v1
	v_or_b32_e32 v85, v3, v2
	v_ashrrev_i32_e32 v1, 31, v0
	v_bitop3_b32 v2, v20, 7, v16 bitop3:0x48
	v_lshlrev_b64 v[0:1], 11, v[0:1]
	v_lshlrev_b32_e32 v2, 4, v2
	v_readlane_b32 s0, v252, 55
	v_or_b32_e32 v0, v0, v2
	v_readlane_b32 s1, v252, 56
	v_readlane_b32 s4, v252, 59
	v_readlane_b32 s5, v252, 60
	v_lshl_add_u64 v[64:65], s[0:1], 0, v[0:1]
	v_or_b32_e32 v0, s44, v18
	v_add_u32_e32 v0, v0, v19
	v_ashrrev_i32_e32 v1, 31, v0
	v_lshlrev_b64 v[0:1], 11, v[0:1]
	v_or_b32_e32 v0, v0, v2
	v_or_b32_e32 v3, 32, v18
	v_lshl_add_u64 v[66:67], s[4:5], 0, v[0:1]
	v_or_b32_e32 v0, s42, v3
	v_add_u32_e32 v0, v0, v19
	v_ashrrev_i32_e32 v1, 31, v0
	v_lshlrev_b64 v[0:1], 11, v[0:1]
	v_or_b32_e32 v0, v0, v2
	v_lshl_add_u64 v[68:69], s[0:1], 0, v[0:1]
	v_or_b32_e32 v0, s44, v3
	v_add_u32_e32 v0, v0, v19
	v_ashrrev_i32_e32 v1, 31, v0
	v_lshlrev_b64 v[0:1], 11, v[0:1]
	v_or_b32_e32 v0, v0, v2
	v_or_b32_e32 v3, 64, v18
	v_lshl_add_u64 v[70:71], s[4:5], 0, v[0:1]
	v_or_b32_e32 v0, s42, v3
	v_add_u32_e32 v0, v0, v19
	v_ashrrev_i32_e32 v1, 31, v0
	v_lshlrev_b64 v[0:1], 11, v[0:1]
	v_or_b32_e32 v0, v0, v2
	v_lshl_add_u64 v[72:73], s[0:1], 0, v[0:1]
	v_or_b32_e32 v0, s44, v3
	v_add_u32_e32 v0, v0, v19
	v_ashrrev_i32_e32 v1, 31, v0
	v_lshlrev_b64 v[0:1], 11, v[0:1]
	v_or_b32_e32 v0, v0, v2
	v_or_b32_e32 v3, 0x60, v18
	v_lshl_add_u64 v[74:75], s[4:5], 0, v[0:1]
	v_or_b32_e32 v0, s42, v3
	v_add_u32_e32 v0, v0, v19
	v_ashrrev_i32_e32 v1, 31, v0
	v_lshlrev_b64 v[0:1], 11, v[0:1]
	v_or_b32_e32 v0, v0, v2
	v_lshl_add_u64 v[76:77], s[0:1], 0, v[0:1]
	v_or_b32_e32 v0, s44, v3
	v_add_u32_e32 v0, v0, v19
	v_ashrrev_i32_e32 v1, 31, v0
	v_lshlrev_b64 v[0:1], 11, v[0:1]
	s_waitcnt vmcnt(0)
; template <class Epi>
; __device__ __forceinline__ void gemm_tile(const bf16_t* A, int lda, const bf16_t* Bt, int ldb, int K, int m0, int n0, const Epi& epi, char* smem) {
;     ...
;     G_ISSUE(0, 0)
;     asm volatile("s_waitcnt vmcnt(0)" ::: "memory");
;     __syncthreads();
;     for (int kt = 0; kt < nk; ++kt) {
;         const int st = (kt & 1) * 32768;
;         if (kt + 1 < nk) G_ISSUE(((kt + 1) & 1) * 32768, (kt + 1) * 64)
;         {
;             bf16x8 a0[4], b0[4], a1[4], b1[4];
;             const int ch0 = ((0 + fq) ^ rsw) << 4, ch1 = ((4 + fq) ^ rsw) << 4;
; #pragma unroll
;             for (int m = 0; m < 4; ++m) a0[m] = *(const bf16x8*)(smem + st + aofs + m * 2048 + ch0);
; #pragma unroll
;             for (int n = 0; n < 4; ++n) b0[n] = *(const bf16x8*)(smem + st + bofs + n * 2048 + ch0);
;             __builtin_amdgcn_sched_barrier(0);
; #pragma unroll
;             for (int m = 0; m < 4; ++m) a1[m] = *(const bf16x8*)(smem + st + aofs + m * 2048 + ch1);
; #pragma unroll
;             for (int n = 0; n < 4; ++n) b1[n] = *(const bf16x8*)(smem + st + bofs + n * 2048 + ch1);
;             __builtin_amdgcn_sched_barrier(0);
;             __builtin_amdgcn_s_setprio(1);
; #pragma unroll
;             for (int m = 0; m < 4; ++m)
; #pragma unroll
;                 for (int n = 0; n < 4; ++n) acc[m][n] = __builtin_amdgcn_mfma_f32_16x16x32_bf16(b0[n], a0[m], acc[m][n], 0, 0, 0);
;             __builtin_amdgcn_sched_barrier(0);
; #pragma unroll
;             for (int m = 0; m < 4; ++m)
; #pragma unroll
;                 for (int n = 0; n < 4; ++n) acc[m][n] = __builtin_amdgcn_mfma_f32_16x16x32_bf16(b1[n], a1[m], acc[m][n], 0, 0, 0);
;             __builtin_amdgcn_s_setprio(0);
;             __builtin_amdgcn_sched_barrier(0);
;         }
;         asm volatile("s_waitcnt vmcnt(0)" ::: "memory");
;         __syncthreads();
	v_or_b32_e32 v0, v0, v2
	v_lshl_add_u64 v[78:79], s[4:5], 0, v[0:1]
	v_mov_b32_e32 v0, 0
	s_mov_b64 s[0:1], 0
	s_mov_b32 s43, 0x8000
	v_mov_b32_e32 v1, v0
	v_mov_b32_e32 v2, v0
	v_mov_b32_e32 v3, v0
	v_mov_b32_e32 v4, v0
	v_mov_b32_e32 v5, v0
	v_mov_b32_e32 v6, v0
	v_mov_b32_e32 v7, v0
	v_mov_b32_e32 v8, v0
	v_mov_b32_e32 v9, v0
	v_mov_b32_e32 v10, v0
	v_mov_b32_e32 v11, v0
	v_mov_b32_e32 v12, v0
	v_mov_b32_e32 v13, v0
	v_mov_b32_e32 v14, v0
	v_mov_b32_e32 v15, v0
	v_mov_b32_e32 v16, v0
	v_mov_b32_e32 v17, v0
	v_mov_b32_e32 v18, v0
	v_mov_b32_e32 v19, v0
	v_mov_b32_e32 v20, v0
	v_mov_b32_e32 v21, v0
	v_mov_b32_e32 v22, v0
	v_mov_b32_e32 v23, v0
	v_mov_b32_e32 v24, v0
	v_mov_b32_e32 v25, v0
	v_mov_b32_e32 v26, v0
	v_mov_b32_e32 v27, v0
	v_mov_b32_e32 v36, v0
	v_mov_b32_e32 v37, v0
	v_mov_b32_e32 v38, v0
	v_mov_b32_e32 v39, v0
	v_mov_b32_e32 v28, v0
	v_mov_b32_e32 v29, v0
	v_mov_b32_e32 v30, v0
	v_mov_b32_e32 v31, v0
	v_mov_b32_e32 v32, v0
	v_mov_b32_e32 v33, v0
	v_mov_b32_e32 v34, v0
	v_mov_b32_e32 v35, v0
	v_mov_b32_e32 v40, v0
	v_mov_b32_e32 v41, v0
	v_mov_b32_e32 v42, v0
	v_mov_b32_e32 v43, v0
	v_mov_b32_e32 v44, v0
	v_mov_b32_e32 v45, v0
	v_mov_b32_e32 v46, v0
	v_mov_b32_e32 v47, v0
	v_mov_b32_e32 v48, v0
	v_mov_b32_e32 v49, v0
	v_mov_b32_e32 v50, v0
	v_mov_b32_e32 v51, v0
	v_mov_b32_e32 v52, v0
	v_mov_b32_e32 v53, v0
	v_mov_b32_e32 v54, v0
	v_mov_b32_e32 v55, v0
	v_mov_b32_e32 v56, v0
	v_mov_b32_e32 v57, v0
	v_mov_b32_e32 v58, v0
	v_mov_b32_e32 v59, v0
	v_mov_b32_e32 v60, v0
	v_mov_b32_e32 v61, v0
	v_mov_b32_e32 v62, v0
	v_mov_b32_e32 v63, v0
	v_readfirstlane_b32 s98, v84
	s_mov_b64 s[100:101], 0
	s_nop 3
	s_add_u32 s99, s98, 0x8000
	s_mov_b32 m0, s99
	v_lshl_add_u64 v[166:167], v[64:65], 0, s[100:101]
	global_load_lds_dwordx4 v[166:167], off
	s_add_u32 m0, s99, 0x1000
	v_lshl_add_u64 v[166:167], v[68:69], 0, s[100:101]
	global_load_lds_dwordx4 v[166:167], off
	s_add_u32 m0, s99, 0x2000
	v_lshl_add_u64 v[166:167], v[72:73], 0, s[100:101]
	global_load_lds_dwordx4 v[166:167], off
	s_add_u32 m0, s99, 0x3000
	v_lshl_add_u64 v[166:167], v[76:77], 0, s[100:101]
	global_load_lds_dwordx4 v[166:167], off
	s_add_u32 m0, s99, 0x4000
	v_lshl_add_u64 v[166:167], v[66:67], 0, s[100:101]
	global_load_lds_dwordx4 v[166:167], off
	s_add_u32 m0, s99, 0x5000
	v_lshl_add_u64 v[166:167], v[70:71], 0, s[100:101]
	global_load_lds_dwordx4 v[166:167], off
	s_add_u32 m0, s99, 0x6000
	v_lshl_add_u64 v[166:167], v[74:75], 0, s[100:101]
	global_load_lds_dwordx4 v[166:167], off
	s_add_u32 m0, s99, 0x7000
	v_lshl_add_u64 v[166:167], v[78:79], 0, s[100:101]
	global_load_lds_dwordx4 v[166:167], off
	s_waitcnt vmcnt(8) lgkmcnt(0)
	s_barrier
.LBB0_182:
	s_add_i32 s45, s43, 0xffff8000
	s_and_b32 s45, s45, 0x8000
	v_add_u32_e32 v89, s45, v88
	ds_read_b128 v[90:93], v89
	ds_read_b128 v[94:97], v89 offset:2048
	ds_read_b128 v[98:101], v89 offset:4096
	ds_read_b128 v[114:117], v89 offset:6144
	v_or_b32_e32 v89, s45, v87
	ds_read_b128 v[118:121], v89 offset:16384
	ds_read_b128 v[122:125], v89 offset:18432
	ds_read_b128 v[126:129], v89 offset:20480
	ds_read_b128 v[130:133], v89 offset:22528
	v_add_u32_e32 v89, s45, v86
	ds_read_b128 v[134:137], v89
	ds_read_b128 v[138:141], v89 offset:2048
	ds_read_b128 v[142:145], v89 offset:4096
	ds_read_b128 v[146:149], v89 offset:6144
	v_or_b32_e32 v89, s45, v85
	ds_read_b128 v[150:153], v89 offset:16384
	ds_read_b128 v[154:157], v89 offset:18432
	ds_read_b128 v[158:161], v89 offset:20480
	ds_read_b128 v[162:165], v89 offset:22528
	s_waitcnt lgkmcnt(0)
	s_barrier
	s_cmpk_eq_i32 s0, 0x700
	s_cbranch_scc1 .Lnodma_g182
	s_add_u32 s100, s0, 0x80
	s_addc_u32 s101, s1, 0
	s_add_u32 s99, s98, s45
	s_setprio 1
	v_mfma_f32_16x16x32_bf16 v[36:39], v[118:121], v[90:93], v[36:39]
	v_mfma_f32_16x16x32_bf16 v[24:27], v[122:125], v[90:93], v[24:27]
	v_mfma_f32_16x16x32_bf16 v[20:23], v[126:129], v[90:93], v[20:23]
	v_mfma_f32_16x16x32_bf16 v[16:19], v[130:133], v[90:93], v[16:19]
	s_mov_b32 m0, s99
	v_lshl_add_u64 v[166:167], v[64:65], 0, s[100:101]
	global_load_lds_dwordx4 v[166:167], off
	v_mfma_f32_16x16x32_bf16 v[12:15], v[118:121], v[94:97], v[12:15]
	v_mfma_f32_16x16x32_bf16 v[8:11], v[122:125], v[94:97], v[8:11]
	v_mfma_f32_16x16x32_bf16 v[4:7], v[126:129], v[94:97], v[4:7]
	v_mfma_f32_16x16x32_bf16 v[0:3], v[130:133], v[94:97], v[0:3]
	s_add_u32 m0, s99, 0x1000
	v_lshl_add_u64 v[166:167], v[68:69], 0, s[100:101]
	global_load_lds_dwordx4 v[166:167], off
	v_mfma_f32_16x16x32_bf16 v[28:31], v[118:121], v[98:101], v[28:31]
	v_mfma_f32_16x16x32_bf16 v[32:35], v[122:125], v[98:101], v[32:35]
	v_mfma_f32_16x16x32_bf16 v[40:43], v[126:129], v[98:101], v[40:43]
	v_mfma_f32_16x16x32_bf16 v[44:47], v[130:133], v[98:101], v[44:47]
	s_add_u32 m0, s99, 0x2000
	v_lshl_add_u64 v[166:167], v[72:73], 0, s[100:101]
	global_load_lds_dwordx4 v[166:167], off
	v_mfma_f32_16x16x32_bf16 v[48:51], v[118:121], v[114:117], v[48:51]
	v_mfma_f32_16x16x32_bf16 v[52:55], v[122:125], v[114:117], v[52:55]
	v_mfma_f32_16x16x32_bf16 v[56:59], v[126:129], v[114:117], v[56:59]
	v_mfma_f32_16x16x32_bf16 v[60:63], v[130:133], v[114:117], v[60:63]
	s_add_u32 m0, s99, 0x3000
	v_lshl_add_u64 v[166:167], v[76:77], 0, s[100:101]
	global_load_lds_dwordx4 v[166:167], off
	v_mfma_f32_16x16x32_bf16 v[36:39], v[150:153], v[134:137], v[36:39]
	v_mfma_f32_16x16x32_bf16 v[24:27], v[154:157], v[134:137], v[24:27]
	v_mfma_f32_16x16x32_bf16 v[20:23], v[158:161], v[134:137], v[20:23]
	v_mfma_f32_16x16x32_bf16 v[16:19], v[162:165], v[134:137], v[16:19]
	s_add_u32 m0, s99, 0x4000
	v_lshl_add_u64 v[166:167], v[66:67], 0, s[100:101]
	global_load_lds_dwordx4 v[166:167], off
	v_mfma_f32_16x16x32_bf16 v[12:15], v[150:153], v[138:141], v[12:15]
	v_mfma_f32_16x16x32_bf16 v[8:11], v[154:157], v[138:141], v[8:11]
	v_mfma_f32_16x16x32_bf16 v[4:7], v[158:161], v[138:141], v[4:7]
	v_mfma_f32_16x16x32_bf16 v[0:3], v[162:165], v[138:141], v[0:3]
	s_add_u32 m0, s99, 0x5000
	v_lshl_add_u64 v[166:167], v[70:71], 0, s[100:101]
	global_load_lds_dwordx4 v[166:167], off
	v_mfma_f32_16x16x32_bf16 v[28:31], v[150:153], v[142:145], v[28:31]
	v_mfma_f32_16x16x32_bf16 v[32:35], v[154:157], v[142:145], v[32:35]
	v_mfma_f32_16x16x32_bf16 v[40:43], v[158:161], v[142:145], v[40:43]
	v_mfma_f32_16x16x32_bf16 v[44:47], v[162:165], v[142:145], v[44:47]
	s_add_u32 m0, s99, 0x6000
	v_lshl_add_u64 v[166:167], v[74:75], 0, s[100:101]
	global_load_lds_dwordx4 v[166:167], off
	v_mfma_f32_16x16x32_bf16 v[48:51], v[150:153], v[146:149], v[48:51]
	v_mfma_f32_16x16x32_bf16 v[52:55], v[154:157], v[146:149], v[52:55]
	v_mfma_f32_16x16x32_bf16 v[56:59], v[158:161], v[146:149], v[56:59]
	v_mfma_f32_16x16x32_bf16 v[60:63], v[162:165], v[146:149], v[60:63]
	s_add_u32 m0, s99, 0x7000
	v_lshl_add_u64 v[166:167], v[78:79], 0, s[100:101]
	global_load_lds_dwordx4 v[166:167], off
	s_setprio 0
	s_branch .Ljoin_g182

; __device__ __forceinline__ int opaque_tid() { int t = threadIdx.x; asm volatile("" : "+v"(t)); return t; }
; template <class Epi>
; __device__ __forceinline__ void gemm_tile(const bf16_t* A, int lda, const bf16_t* Bt, int ldb, int K, int m0, int n0, const Epi& epi, char* smem) {
;     const int tid = opaque_tid(), lane = tid & 63, wid = tid >> 6, wr = wid >> 1, wc = wid & 1, fr = lane & 15, fq = lane >> 4;
;     f32x4 acc[4][4];
; #pragma unroll
;     for (int m = 0; m < 4; ++m)
; #pragma unroll
;         for (int n = 0; n < 4; ++n) acc[m][n] = (f32x4){0.f, 0.f, 0.f, 0.f};
;     const int lr = lane >> 3;
;     const bf16_t* Ag[4]; const bf16_t* Bg[4];
; #pragma unroll
;     for (int i = 0; i < 4; ++i) {
;         const int r = (wid + 4 * i) * 8 + lr, lc = (lane & 7) ^ ((r >> 1) & 7);
;         Ag[i] = A + (size_t)(m0 + r) * lda + lc * 8; Bg[i] = Bt + (size_t)(n0 + r) * ldb + lc * 8;
;     }
;     const unsigned lds0 = (unsigned)(uintptr_t)smem;
;     const int rsw = (fr >> 1) & 7;
;     const int aofs = (wr * 64 + fr) * 128, bofs = 16384 + (wc * 64 + fr) * 128;
;     const int nk = K >> 6;
;     ...
;     G_ISSUE(0, 0)
;     asm volatile("s_waitcnt vmcnt(0)" ::: "memory");
;     __syncthreads();
.LBB0_696:
	v_mov_b32_e32 v16, v109
	s_lshl_b32 s30, s53, 7
	v_ashrrev_i32_e32 v17, 6, v16
	v_bfe_u32 v18, v16, 3, 3
	v_lshlrev_b32_e32 v19, 3, v17
	v_or_b32_e32 v12, v19, v18
	v_lshrrev_b32_e32 v20, 1, v12
	v_add_u32_e32 v0, s30, v12
	v_xor_b32_e32 v2, v20, v16
	s_waitcnt lgkmcnt(0)
	v_ashrrev_i32_e32 v1, 31, v0
	s_lshl_b32 s42, s52, 7
	v_lshlrev_b64 v[0:1], 11, v[0:1]
	v_lshlrev_b32_e32 v2, 4, v2
	v_lshlrev_b32_e32 v85, 10, v17
	v_lshl_add_u64 v[0:1], s[40:41], 0, v[0:1]
	v_and_b32_e32 v104, 0x70, v2
	v_add_u32_e32 v2, s42, v12
	v_add_u32_e32 v6, 32, v12
	v_readfirstlane_b32 s0, v85
	v_lshl_add_u64 v[0:1], v[0:1], 0, v[104:105]
	v_ashrrev_i32_e32 v3, 31, v2
	s_mov_b64 s[4:5], s[20:21]
	v_add_u32_e32 v4, s30, v6
	s_mov_b32 m0, s0
	v_lshlrev_b64 v[2:3], 11, v[2:3]
	s_mov_b64 s[10:11], s[26:27]
	v_ashrrev_i32_e32 v5, 31, v4
	v_add_u32_e32 v6, s42, v6
	v_add_u32_e32 v10, 64, v12
	global_load_lds_dwordx4 v[0:1], off
	v_add_u32_e32 v0, 0x4000, v85
	v_lshl_add_u64 v[2:3], s[10:11], 0, v[2:3]
	v_lshlrev_b64 v[4:5], 11, v[4:5]
	v_ashrrev_i32_e32 v7, 31, v6
	v_add_u32_e32 v8, s30, v10
	v_readfirstlane_b32 s0, v0
	v_add_u32_e32 v0, 0x1000, v85
	v_lshl_add_u64 v[2:3], v[2:3], 0, v[104:105]
	v_lshl_add_u64 v[4:5], s[40:41], 0, v[4:5]
	v_lshlrev_b64 v[6:7], 11, v[6:7]
	v_ashrrev_i32_e32 v9, 31, v8
	v_add_u32_e32 v10, s42, v10
	v_add_u32_e32 v14, 0x60, v12
	s_mov_b32 m0, s0
	v_readfirstlane_b32 s0, v0
	v_add_u32_e32 v0, 0x5000, v85
	v_lshl_add_u64 v[4:5], v[4:5], 0, v[104:105]
	v_lshl_add_u64 v[6:7], s[10:11], 0, v[6:7]
	v_lshlrev_b64 v[8:9], 11, v[8:9]
	v_ashrrev_i32_e32 v11, 31, v10
	v_add_u32_e32 v12, s30, v14
	global_load_lds_dwordx4 v[2:3], off
	s_mov_b32 m0, s0
	v_readfirstlane_b32 s0, v0
	v_add_u32_e32 v0, 0x2000, v85
	v_lshl_add_u64 v[6:7], v[6:7], 0, v[104:105]
	v_lshl_add_u64 v[8:9], s[40:41], 0, v[8:9]
	v_lshlrev_b64 v[10:11], 11, v[10:11]
	v_ashrrev_i32_e32 v13, 31, v12
	v_add_u32_e32 v14, s42, v14
	global_load_lds_dwordx4 v[4:5], off
	s_mov_b32 m0, s0
	v_readfirstlane_b32 s0, v0
	v_add_u32_e32 v0, 0x6000, v85
	v_lshl_add_u64 v[8:9], v[8:9], 0, v[104:105]
	v_lshl_add_u64 v[10:11], s[10:11], 0, v[10:11]
	v_lshlrev_b64 v[12:13], 11, v[12:13]
	v_ashrrev_i32_e32 v15, 31, v14
	global_load_lds_dwordx4 v[6:7], off
	s_mov_b32 m0, s0
	v_readfirstlane_b32 s0, v0
	v_add_u32_e32 v0, 0x3000, v85
	v_lshl_add_u64 v[10:11], v[10:11], 0, v[104:105]
	v_lshl_add_u64 v[12:13], s[40:41], 0, v[12:13]
	v_lshlrev_b64 v[14:15], 11, v[14:15]
	global_load_lds_dwordx4 v[8:9], off
	s_mov_b32 m0, s0
	v_readfirstlane_b32 s0, v0
	v_add_u32_e32 v0, 0x7000, v85
	v_lshl_add_u64 v[12:13], v[12:13], 0, v[104:105]
	v_lshl_add_u64 v[14:15], s[10:11], 0, v[14:15]
	global_load_lds_dwordx4 v[10:11], off
	s_mov_b32 m0, s0
	v_readfirstlane_b32 s0, v0
	v_lshl_add_u64 v[14:15], v[14:15], 0, v[104:105]
	global_load_lds_dwordx4 v[12:13], off
	s_mov_b32 m0, s0
	v_and_b32_e32 v83, 15, v16
	global_load_lds_dwordx4 v[14:15], off
	v_lshrrev_b32_e32 v21, 1, v16
	v_bfe_u32 v84, v16, 4, 2
	v_ashrrev_i32_e32 v82, 7, v16
	v_and_b32_e32 v80, 1, v17
	v_lshlrev_b32_e32 v23, 7, v83
	v_bitop3_b32 v0, v84, v21, 7 bitop3:0x78
	v_bfe_u32 v22, v16, 1, 3
	v_lshlrev_b32_e32 v0, 4, v0
	v_lshl_or_b32 v2, v82, 13, v23
	v_lshl_or_b32 v3, v80, 13, v23
	v_bitop3_b32 v1, v84, v22, 4 bitop3:0x36
	v_or_b32_e32 v88, v2, v0
	v_or_b32_e32 v89, v3, v0
	v_or_b32_e32 v0, s30, v18
	v_lshlrev_b32_e32 v1, 4, v1
	v_add_u32_e32 v0, v0, v19
	v_or_b32_e32 v87, v2, v1
	v_or_b32_e32 v86, v3, v1
	v_ashrrev_i32_e32 v1, 31, v0
	v_bitop3_b32 v2, v20, 7, v16 bitop3:0x48
	v_lshlrev_b64 v[0:1], 11, v[0:1]
	v_lshlrev_b32_e32 v2, 4, v2
	v_readlane_b32 s0, v252, 55
	v_or_b32_e32 v0, v0, v2
	v_readlane_b32 s1, v252, 56
	v_readlane_b32 s4, v253, 0
	v_readlane_b32 s5, v253, 1
	v_lshl_add_u64 v[64:65], s[0:1], 0, v[0:1]
	v_or_b32_e32 v0, s42, v18
	v_add_u32_e32 v0, v0, v19
	v_ashrrev_i32_e32 v1, 31, v0
	v_lshlrev_b64 v[0:1], 11, v[0:1]
	v_or_b32_e32 v0, v0, v2
	v_or_b32_e32 v3, 32, v18
	v_lshl_add_u64 v[66:67], s[4:5], 0, v[0:1]
	v_or_b32_e32 v0, s30, v3
	v_add_u32_e32 v0, v0, v19
	v_ashrrev_i32_e32 v1, 31, v0
	v_lshlrev_b64 v[0:1], 11, v[0:1]
	v_or_b32_e32 v0, v0, v2
	v_lshl_add_u64 v[68:69], s[0:1], 0, v[0:1]
	v_or_b32_e32 v0, s42, v3
	v_add_u32_e32 v0, v0, v19
	v_ashrrev_i32_e32 v1, 31, v0
	v_lshlrev_b64 v[0:1], 11, v[0:1]
	v_or_b32_e32 v0, v0, v2
	v_or_b32_e32 v3, 64, v18
	v_lshl_add_u64 v[70:71], s[4:5], 0, v[0:1]
	v_or_b32_e32 v0, s30, v3
	v_add_u32_e32 v0, v0, v19
	v_ashrrev_i32_e32 v1, 31, v0
	v_lshlrev_b64 v[0:1], 11, v[0:1]
	v_or_b32_e32 v0, v0, v2
	v_lshl_add_u64 v[72:73], s[0:1], 0, v[0:1]
	v_or_b32_e32 v0, s42, v3
	v_add_u32_e32 v0, v0, v19
	v_ashrrev_i32_e32 v1, 31, v0
	v_lshlrev_b64 v[0:1], 11, v[0:1]
	v_or_b32_e32 v0, v0, v2
	v_or_b32_e32 v3, 0x60, v18
	v_lshl_add_u64 v[74:75], s[4:5], 0, v[0:1]
	v_or_b32_e32 v0, s30, v3
	v_add_u32_e32 v0, v0, v19
	v_ashrrev_i32_e32 v1, 31, v0
	v_lshlrev_b64 v[0:1], 11, v[0:1]
	v_or_b32_e32 v0, v0, v2
	v_lshl_add_u64 v[76:77], s[0:1], 0, v[0:1]
	v_or_b32_e32 v0, s42, v3
	v_add_u32_e32 v0, v0, v19
	v_ashrrev_i32_e32 v1, 31, v0
	v_lshlrev_b64 v[0:1], 11, v[0:1]
	s_waitcnt vmcnt(0)
; template <class Epi>
; __device__ __forceinline__ void gemm_tile(const bf16_t* A, int lda, const bf16_t* Bt, int ldb, int K, int m0, int n0, const Epi& epi, char* smem) {
;     ...
;     G_ISSUE(0, 0)
;     asm volatile("s_waitcnt vmcnt(0)" ::: "memory");
;     __syncthreads();
;     for (int kt = 0; kt < nk; ++kt) {
;         const int st = (kt & 1) * 32768;
;         if (kt + 1 < nk) G_ISSUE(((kt + 1) & 1) * 32768, (kt + 1) * 64)
;         {
;             bf16x8 a0[4], b0[4], a1[4], b1[4];
;             const int ch0 = ((0 + fq) ^ rsw) << 4, ch1 = ((4 + fq) ^ rsw) << 4;
; #pragma unroll
;             for (int m = 0; m < 4; ++m) a0[m] = *(const bf16x8*)(smem + st + aofs + m * 2048 + ch0);
; #pragma unroll
;             for (int n = 0; n < 4; ++n) b0[n] = *(const bf16x8*)(smem + st + bofs + n * 2048 + ch0);
;             __builtin_amdgcn_sched_barrier(0);
; #pragma unroll
;             for (int m = 0; m < 4; ++m) a1[m] = *(const bf16x8*)(smem + st + aofs + m * 2048 + ch1);
; #pragma unroll
;             for (int n = 0; n < 4; ++n) b1[n] = *(const bf16x8*)(smem + st + bofs + n * 2048 + ch1);
;             __builtin_amdgcn_sched_barrier(0);
;             __builtin_amdgcn_s_setprio(1);
; #pragma unroll
;             for (int m = 0; m < 4; ++m)
; #pragma unroll
;                 for (int n = 0; n < 4; ++n) acc[m][n] = __builtin_amdgcn_mfma_f32_16x16x32_bf16(b0[n], a0[m], acc[m][n], 0, 0, 0);
;             __builtin_amdgcn_sched_barrier(0);
; #pragma unroll
;             for (int m = 0; m < 4; ++m)
; #pragma unroll
;                 for (int n = 0; n < 4; ++n) acc[m][n] = __builtin_amdgcn_mfma_f32_16x16x32_bf16(b1[n], a1[m], acc[m][n], 0, 0, 0);
;             __builtin_amdgcn_s_setprio(0);
;             __builtin_amdgcn_sched_barrier(0);
;         }
;         asm volatile("s_waitcnt vmcnt(0)" ::: "memory");
;         __syncthreads();
	v_or_b32_e32 v0, v0, v2
	v_lshl_add_u64 v[78:79], s[4:5], 0, v[0:1]
	v_mov_b32_e32 v0, 0
	v_and_b32_e32 v81, 63, v16
	s_mov_b64 s[0:1], 0
	s_mov_b32 s31, 0x8000
	v_mov_b32_e32 v1, v0
	v_mov_b32_e32 v2, v0
	v_mov_b32_e32 v3, v0
	v_mov_b32_e32 v4, v0
	v_mov_b32_e32 v5, v0
	v_mov_b32_e32 v6, v0
	v_mov_b32_e32 v7, v0
	v_mov_b32_e32 v8, v0
	v_mov_b32_e32 v9, v0
	v_mov_b32_e32 v10, v0
	v_mov_b32_e32 v11, v0
	v_mov_b32_e32 v12, v0
	v_mov_b32_e32 v13, v0
	v_mov_b32_e32 v14, v0
	v_mov_b32_e32 v15, v0
	v_mov_b32_e32 v16, v0
	v_mov_b32_e32 v17, v0
	v_mov_b32_e32 v18, v0
	v_mov_b32_e32 v19, v0
	v_mov_b32_e32 v20, v0
	v_mov_b32_e32 v21, v0
	v_mov_b32_e32 v22, v0
	v_mov_b32_e32 v23, v0
	v_mov_b32_e32 v24, v0
	v_mov_b32_e32 v25, v0
	v_mov_b32_e32 v26, v0
	v_mov_b32_e32 v27, v0
	v_mov_b32_e32 v36, v0
	v_mov_b32_e32 v37, v0
	v_mov_b32_e32 v38, v0
	v_mov_b32_e32 v39, v0
	v_mov_b32_e32 v28, v0
	v_mov_b32_e32 v29, v0
	v_mov_b32_e32 v30, v0
	v_mov_b32_e32 v31, v0
	v_mov_b32_e32 v32, v0
	v_mov_b32_e32 v33, v0
	v_mov_b32_e32 v34, v0
	v_mov_b32_e32 v35, v0
	v_mov_b32_e32 v40, v0
	v_mov_b32_e32 v41, v0
	v_mov_b32_e32 v42, v0
	v_mov_b32_e32 v43, v0
	v_mov_b32_e32 v44, v0
	v_mov_b32_e32 v45, v0
	v_mov_b32_e32 v46, v0
	v_mov_b32_e32 v47, v0
	v_mov_b32_e32 v48, v0
	v_mov_b32_e32 v49, v0
	v_mov_b32_e32 v50, v0
	v_mov_b32_e32 v51, v0
	v_mov_b32_e32 v52, v0
	v_mov_b32_e32 v53, v0
	v_mov_b32_e32 v54, v0
	v_mov_b32_e32 v55, v0
	v_mov_b32_e32 v56, v0
	v_mov_b32_e32 v57, v0
	v_mov_b32_e32 v58, v0
	v_mov_b32_e32 v59, v0
	v_mov_b32_e32 v60, v0
	v_mov_b32_e32 v61, v0
	v_mov_b32_e32 v62, v0
	v_mov_b32_e32 v63, v0
	s_mov_b64 s[6:7], s[22:23]
	s_mov_b64 s[8:9], s[24:25]
	v_readfirstlane_b32 s98, v85
	s_mov_b64 s[100:101], 0
	s_nop 3
	s_add_u32 s99, s98, 0x8000
	s_mov_b32 m0, s99
	v_lshl_add_u64 v[166:167], v[64:65], 0, s[100:101]
	global_load_lds_dwordx4 v[166:167], off
	s_add_u32 m0, s99, 0x1000
	v_lshl_add_u64 v[166:167], v[68:69], 0, s[100:101]
	global_load_lds_dwordx4 v[166:167], off
	s_add_u32 m0, s99, 0x2000
	v_lshl_add_u64 v[166:167], v[72:73], 0, s[100:101]
	global_load_lds_dwordx4 v[166:167], off
	s_add_u32 m0, s99, 0x3000
	v_lshl_add_u64 v[166:167], v[76:77], 0, s[100:101]
	global_load_lds_dwordx4 v[166:167], off
	s_add_u32 m0, s99, 0x4000
	v_lshl_add_u64 v[166:167], v[66:67], 0, s[100:101]
	global_load_lds_dwordx4 v[166:167], off
	s_add_u32 m0, s99, 0x5000
	v_lshl_add_u64 v[166:167], v[70:71], 0, s[100:101]
	global_load_lds_dwordx4 v[166:167], off
	s_add_u32 m0, s99, 0x6000
	v_lshl_add_u64 v[166:167], v[74:75], 0, s[100:101]
	global_load_lds_dwordx4 v[166:167], off
	s_add_u32 m0, s99, 0x7000
	v_lshl_add_u64 v[166:167], v[78:79], 0, s[100:101]
	global_load_lds_dwordx4 v[166:167], off
	s_waitcnt vmcnt(8) lgkmcnt(0)
	s_barrier
.LBB0_697:
	s_add_i32 s34, s31, 0xffff8000
	s_and_b32 s34, s34, 0x8000
	v_add_u32_e32 v102, s34, v88
	ds_read_b128 v[90:93], v102
	ds_read_b128 v[94:97], v102 offset:2048
	ds_read_b128 v[98:101], v102 offset:4096
	ds_read_b128 v[114:117], v102 offset:6144
	v_or_b32_e32 v102, s34, v89
	ds_read_b128 v[118:121], v102 offset:16384
	ds_read_b128 v[122:125], v102 offset:18432
	ds_read_b128 v[126:129], v102 offset:20480
	ds_read_b128 v[130:133], v102 offset:22528
	v_add_u32_e32 v102, s34, v87
	ds_read_b128 v[134:137], v102
	ds_read_b128 v[138:141], v102 offset:2048
	ds_read_b128 v[142:145], v102 offset:4096
	ds_read_b128 v[146:149], v102 offset:6144
	v_or_b32_e32 v102, s34, v86
	ds_read_b128 v[150:153], v102 offset:16384
	ds_read_b128 v[154:157], v102 offset:18432
	ds_read_b128 v[158:161], v102 offset:20480
	ds_read_b128 v[162:165], v102 offset:22528
	s_waitcnt lgkmcnt(0)
	s_barrier
	s_cmpk_eq_i32 s0, 0x700
	s_cbranch_scc1 .Lnodma_g697
	s_add_u32 s100, s0, 0x80
	s_addc_u32 s101, s1, 0
	s_add_u32 s99, s98, s34
	s_setprio 1
	v_mfma_f32_16x16x32_bf16 v[36:39], v[118:121], v[90:93], v[36:39]
	v_mfma_f32_16x16x32_bf16 v[24:27], v[122:125], v[90:93], v[24:27]
	v_mfma_f32_16x16x32_bf16 v[20:23], v[126:129], v[90:93], v[20:23]
	v_mfma_f32_16x16x32_bf16 v[16:19], v[130:133], v[90:93], v[16:19]
	s_mov_b32 m0, s99
	v_lshl_add_u64 v[166:167], v[64:65], 0, s[100:101]
	global_load_lds_dwordx4 v[166:167], off
	v_mfma_f32_16x16x32_bf16 v[12:15], v[118:121], v[94:97], v[12:15]
	v_mfma_f32_16x16x32_bf16 v[8:11], v[122:125], v[94:97], v[8:11]
	v_mfma_f32_16x16x32_bf16 v[4:7], v[126:129], v[94:97], v[4:7]
	v_mfma_f32_16x16x32_bf16 v[0:3], v[130:133], v[94:97], v[0:3]
	s_add_u32 m0, s99, 0x1000
	v_lshl_add_u64 v[166:167], v[68:69], 0, s[100:101]
	global_load_lds_dwordx4 v[166:167], off
	v_mfma_f32_16x16x32_bf16 v[28:31], v[118:121], v[98:101], v[28:31]
	v_mfma_f32_16x16x32_bf16 v[32:35], v[122:125], v[98:101], v[32:35]
	v_mfma_f32_16x16x32_bf16 v[40:43], v[126:129], v[98:101], v[40:43]
	v_mfma_f32_16x16x32_bf16 v[44:47], v[130:133], v[98:101], v[44:47]
	s_add_u32 m0, s99, 0x2000
	v_lshl_add_u64 v[166:167], v[72:73], 0, s[100:101]
	global_load_lds_dwordx4 v[166:167], off
	v_mfma_f32_16x16x32_bf16 v[48:51], v[118:121], v[114:117], v[48:51]
	v_mfma_f32_16x16x32_bf16 v[52:55], v[122:125], v[114:117], v[52:55]
	v_mfma_f32_16x16x32_bf16 v[56:59], v[126:129], v[114:117], v[56:59]
	v_mfma_f32_16x16x32_bf16 v[60:63], v[130:133], v[114:117], v[60:63]
	s_add_u32 m0, s99, 0x3000
	v_lshl_add_u64 v[166:167], v[76:77], 0, s[100:101]
	global_load_lds_dwordx4 v[166:167], off
	v_mfma_f32_16x16x32_bf16 v[36:39], v[150:153], v[134:137], v[36:39]
	v_mfma_f32_16x16x32_bf16 v[24:27], v[154:157], v[134:137], v[24:27]
	v_mfma_f32_16x16x32_bf16 v[20:23], v[158:161], v[134:137], v[20:23]
	v_mfma_f32_16x16x32_bf16 v[16:19], v[162:165], v[134:137], v[16:19]
	s_add_u32 m0, s99, 0x4000
	v_lshl_add_u64 v[166:167], v[66:67], 0, s[100:101]
	global_load_lds_dwordx4 v[166:167], off
	v_mfma_f32_16x16x32_bf16 v[12:15], v[150:153], v[138:141], v[12:15]
	v_mfma_f32_16x16x32_bf16 v[8:11], v[154:157], v[138:141], v[8:11]
	v_mfma_f32_16x16x32_bf16 v[4:7], v[158:161], v[138:141], v[4:7]
	v_mfma_f32_16x16x32_bf16 v[0:3], v[162:165], v[138:141], v[0:3]
	s_add_u32 m0, s99, 0x5000
	v_lshl_add_u64 v[166:167], v[70:71], 0, s[100:101]
	global_load_lds_dwordx4 v[166:167], off
	v_mfma_f32_16x16x32_bf16 v[28:31], v[150:153], v[142:145], v[28:31]
	v_mfma_f32_16x16x32_bf16 v[32:35], v[154:157], v[142:145], v[32:35]
	v_mfma_f32_16x16x32_bf16 v[40:43], v[158:161], v[142:145], v[40:43]
	v_mfma_f32_16x16x32_bf16 v[44:47], v[162:165], v[142:145], v[44:47]
	s_add_u32 m0, s99, 0x6000
	v_lshl_add_u64 v[166:167], v[74:75], 0, s[100:101]
	global_load_lds_dwordx4 v[166:167], off
	v_mfma_f32_16x16x32_bf16 v[48:51], v[150:153], v[146:149], v[48:51]
	v_mfma_f32_16x16x32_bf16 v[52:55], v[154:157], v[146:149], v[52:55]
	v_mfma_f32_16x16x32_bf16 v[56:59], v[158:161], v[146:149], v[56:59]
	v_mfma_f32_16x16x32_bf16 v[60:63], v[162:165], v[146:149], v[60:63]
	s_add_u32 m0, s99, 0x7000
	v_lshl_add_u64 v[166:167], v[78:79], 0, s[100:101]
	global_load_lds_dwordx4 v[166:167], off
	s_setprio 0
	s_branch .Ljoin_g697
